# phase 3 ssdA head loop: all global loads of a head issued together, x tile kept in registers across both scan directions
# speedup vs baseline: 1.0053x; 1.0033x over previous
; DI void ssdA_item(const Params& p, int layer, int it, unsigned char* smem) {
;     ...
;     { const int t = tid & 127, d = tid >> 7; const float dt = DT[(size_t)(r0 + t) * 12 + d * 6 + hd]; const float a = -__expf(p.in[I_ALOG][layer * 12 + d * 6 + hd]); dtv[d * 128 + t] = dt; av[d * 128 + t] = dt * a; }
;     { bf16x8 sv[4];
; #pragma unroll
;       for (int q = 0; q < 4; ++q) { const int i = tid + 256 * q, t = i >> 3, c8 = i & 7; sv[q] = ld8(UZ + (size_t)(r0 + t) * 1024 + 384 + g * 64 + c8 * 8); }
; #pragma unroll
;       for (int q = 0; q < 4; ++q) { const int i = tid + 256 * q, t = i >> 3, c8 = i & 7;
; #pragma unroll
;         for (int j = 0; j < 8; ++j) BT[(c8 * 8 + j) * TS + t] = (bf16_t)sv[q][j]; } }
;     __syncthreads();
;     ...
;           for (int q = 0; q < 4; ++q) { const int i = tid + 256 * q, t = i >> 3, c8 = i & 7; sv[q] = ld8(UZ + (size_t)(r0 + t) * 1024 + hd * 64 + c8 * 8); }
.LBB0_1542:
	s_mul_hi_u32 s0, s37, 0x2aaaaaab
	s_mul_i32 s0, s0, 6
	v_and_b32_e32 v0, 0x7f, v10
	v_ashrrev_i32_e32 v12, 7, v10
	s_sub_i32 s42, s37, s0
	v_add_u32_e32 v2, s36, v0
	v_mul_lo_u32 v0, v12, 6
	s_add_i32 s37, s42, s14
	v_ashrrev_i32_e32 v1, 31, v0
	v_mad_u64_u32 v[4:5], s[0:1], v2, 48, s[30:31]
	v_lshl_add_u64 v[4:5], v[0:1], 2, v[4:5]
	v_add_u32_e32 v0, s37, v0
	v_readlane_b32 s44, v255, 7
	v_ashrrev_i32_e32 v1, 31, v0
	v_readlane_b32 s48, v255, 11
	v_readlane_b32 s49, v255, 12
	s_barrier
	s_nop 0
	v_lshl_add_u64 v[0:1], v[0:1], 2, s[48:49]
	global_load_dword v153, v[0:1], off
	s_lshl_b32 s72, s42, 2
	v_lshl_add_u64 v[4:5], v[4:5], 0, s[72:73]
	global_load_dword v154, v[4:5], off
	v_lshl_add_u32 v155, v10, 2, 0
	v_ashrrev_i32_e32 v28, 3, v10
	s_cmp_gt_u32 s42, 2
	s_cselect_b32 s72, 0x80, 0
	v_ashrrev_i32_e32 v11, 6, v10
	v_and_b32_e32 v13, 63, v10
	v_cmp_gt_i32_e32 vcc, 2, v11
	v_readlane_b32 s45, v255, 8
	v_readlane_b32 s46, v255, 9
	v_readlane_b32 s47, v255, 10
	v_readlane_b32 s50, v255, 13
	v_readlane_b32 s51, v255, 14
	v_readlane_b32 s52, v255, 15
	v_readlane_b32 s53, v255, 16
	v_readlane_b32 s54, v255, 17
	v_readlane_b32 s55, v255, 18
	v_readlane_b32 s56, v255, 19
	v_readlane_b32 s57, v255, 20
	v_readlane_b32 s58, v255, 21
	v_readlane_b32 s59, v255, 22
	v_lshlrev_b32_e32 v0, 3, v10
	v_and_b32_e32 v14, 56, v0
	v_add_u32_e32 v0, s36, v28
	v_ashrrev_i32_e32 v1, 31, v0
	v_lshlrev_b64 v[0:1], 11, v[0:1]
	v_lshl_add_u64 v[4:5], s[34:35], 0, v[0:1]
	v_lshl_add_u64 v[4:5], v[4:5], 0, s[72:73]
	v_lshlrev_b32_e32 v2, 1, v14
	v_lshl_add_u64 v[4:5], v[4:5], 0, v[2:3]
	global_load_dwordx4 v[16:19], v[4:5], off offset:768
	v_add_u32_e32 v4, 0x100, v10
	v_ashrrev_i32_e32 v29, 3, v4
	v_add_u32_e32 v4, s36, v29
	v_ashrrev_i32_e32 v5, 31, v4
	v_lshlrev_b64 v[4:5], 11, v[4:5]
	v_lshl_add_u64 v[6:7], s[34:35], 0, v[4:5]
	v_lshl_add_u64 v[6:7], v[6:7], 0, s[72:73]
	v_lshl_add_u64 v[6:7], v[6:7], 0, v[2:3]
	global_load_dwordx4 v[20:23], v[6:7], off offset:768
	v_add_u32_e32 v6, 0x200, v10
	v_ashrrev_i32_e32 v30, 3, v6
	v_add_u32_e32 v6, s36, v30
	v_ashrrev_i32_e32 v7, 31, v6
	v_lshlrev_b64 v[6:7], 11, v[6:7]
	v_lshl_add_u64 v[8:9], s[34:35], 0, v[6:7]
	v_lshl_add_u64 v[8:9], v[8:9], 0, s[72:73]
	v_lshl_add_u64 v[8:9], v[8:9], 0, v[2:3]
	global_load_dwordx4 v[24:27], v[8:9], off offset:768
	v_add_u32_e32 v8, 0x300, v10
	v_ashrrev_i32_e32 v31, 3, v8
	v_add_u32_e32 v8, s36, v31
	v_ashrrev_i32_e32 v9, 31, v8
	v_lshlrev_b64 v[8:9], 11, v[8:9]
	v_lshl_add_u64 v[32:33], s[34:35], 0, v[8:9]
	v_lshl_add_u64 v[32:33], v[32:33], 0, s[72:73]
	v_lshl_add_u64 v[32:33], v[32:33], 0, v[2:3]
	global_load_dwordx4 v[36:39], v[32:33], off offset:768
	s_lshl_b32 s0, s42, 7
	s_add_u32 s0, s34, s0
	s_addc_u32 s1, s35, 0
	v_lshl_add_u64 v[156:157], s[0:1], 0, v[2:3]
	v_lshl_add_u64 v[158:159], v[156:157], 0, v[4:5]
	v_lshl_add_u64 v[160:161], v[156:157], 0, v[6:7]
	v_lshl_add_u64 v[162:163], v[156:157], 0, v[8:9]
	v_lshl_add_u64 v[156:157], v[156:157], 0, v[0:1]
	global_load_dwordx4 v[190:193], v[156:157], off
	global_load_dwordx4 v[194:197], v[158:159], off
	global_load_dwordx4 v[198:201], v[160:161], off
	global_load_dwordx4 v[202:205], v[162:163], off
	s_waitcnt vmcnt(9)
	v_mul_f32_e32 v153, 0x3fb8aa3b, v153
	v_exp_f32_e32 v153, v153
	s_waitcnt vmcnt(8)
	v_mul_f32_e64 v153, v154, -v153
	ds_write2st64_b32 v155, v154, v153 offset0:136 offset1:140
	v_lshl_add_u32 v32, v28, 1, 0
	v_mad_u32_u24 v15, v14, s86, v32
	v_lshl_add_u32 v33, v29, 1, 0
	v_lshl_add_u32 v34, v30, 1, 0
	v_lshl_add_u32 v35, v31, 1, 0
	s_waitcnt vmcnt(7)
	ds_write_b16 v15, v16
	ds_write_b16_d16_hi v15, v16 offset:272
	ds_write_b16 v15, v17 offset:544
	ds_write_b16_d16_hi v15, v17 offset:816
	ds_write_b16 v15, v18 offset:1088
	ds_write_b16_d16_hi v15, v18 offset:1360
	ds_write_b16 v15, v19 offset:1632
	ds_write_b16_d16_hi v15, v19 offset:1904
	v_mad_u32_u24 v15, v14, s86, v33
	s_waitcnt vmcnt(6)
	ds_write_b16 v15, v20
	ds_write_b16_d16_hi v15, v20 offset:272
	ds_write_b16 v15, v21 offset:544
	ds_write_b16_d16_hi v15, v21 offset:816
	ds_write_b16 v15, v22 offset:1088
	ds_write_b16_d16_hi v15, v22 offset:1360
	ds_write_b16 v15, v23 offset:1632
	ds_write_b16_d16_hi v15, v23 offset:1904
	v_mad_u32_u24 v15, v14, s86, v34
	s_waitcnt vmcnt(5)
	ds_write_b16 v15, v24
	ds_write_b16_d16_hi v15, v24 offset:272
	ds_write_b16 v15, v25 offset:544
	ds_write_b16_d16_hi v15, v25 offset:816
	ds_write_b16 v15, v26 offset:1088
	ds_write_b16_d16_hi v15, v26 offset:1360
	ds_write_b16 v15, v27 offset:1632
	ds_write_b16_d16_hi v15, v27 offset:1904
	v_mad_u32_u24 v15, v14, s86, v35
	s_waitcnt vmcnt(4)
	ds_write_b16 v15, v36
	ds_write_b16_d16_hi v15, v36 offset:272
	ds_write_b16 v15, v37 offset:544
	ds_write_b16_d16_hi v15, v37 offset:816
	ds_write_b16 v15, v38 offset:1088
	ds_write_b16_d16_hi v15, v38 offset:1360
	ds_write_b16 v15, v39 offset:1632
	ds_write_b16_d16_hi v15, v39 offset:1904
	s_waitcnt lgkmcnt(0)
	s_barrier
; DI float bf2f(bf16_t v) { return __uint_as_float(((unsigned)v) << 16); }
; DI bf16_t f2bf(float x) { unsigned r; asm("v_cvt_pk_bf16_f32 %0, %1, %1" : "=v"(r) : "v"(x)); return (bf16_t)r; }
; DI void wave_scan128(const float* v, float* out, bool reverse, int lane) {
;     const float v0 = v[2 * lane], v1 = v[2 * lane + 1];
;     float s = v0 + v1;
; #pragma unroll
;     for (int o = 1; o < 64; o <<= 1) { float t = __shfl_up(s, o); if (lane >= o) s += t; }
;     const float total = __shfl(s, 63);
;     if (!reverse) { out[2 * lane] = s - v1; out[2 * lane + 1] = s; }
;     else { out[2 * lane] = total - (s - v0 - v1); out[2 * lane + 1] = total - (s - v1); }
; }
; DI void ssdA_item(const Params& p, int layer, int it, unsigned char* smem) {
;     ...
;     if (wave < 2) wave_scan128(av + wave * 128, cum + wave * 128, wave == 1, lane);
;     __syncthreads();
;     float* ST = (float*)(p.ws + stbase(layer)); float* DEC = (float*)(p.ws + stbase(layer) + ST_BYTES);
;     for (int d = 0; d < 2; ++d) {
;         const float total = d == 0 ? cum[127] : cum[128];
;         { bf16x8 sv[4];
; #pragma unroll
;           for (int q = 0; q < 4; ++q) { const int i = tid + 256 * q, t = i >> 3, c8 = i & 7; sv[q] = ld8(UZ + (size_t)(r0 + t) * 1024 + hd * 64 + c8 * 8); }
; #pragma unroll
;           for (int q = 0; q < 4; ++q) { const int i = tid + 256 * q, t = i >> 3, c8 = i & 7;
;             const float w = __expf(total - cum[d * 128 + t]) * dtv[d * 128 + t];
; #pragma unroll
;             for (int j = 0; j < 8; ++j) XT[(c8 * 8 + j) * TS + t] = f2bf(bf2f((bf16_t)sv[q][j]) * w); } }
;         __syncthreads();
;         const int pt = wave >> 1, nt = wave & 1;
	s_and_saveexec_b64 s[0:1], vcc
	s_cbranch_execz .LBB0_1544
	v_lshlrev_b32_e32 v15, 9, v11
	v_lshlrev_b32_e32 v16, 3, v13
	v_add3_u32 v15, 0, v15, v16
	ds_read_b64 v[16:17], v15 offset:35840
	v_and_b32_e32 v18, 64, v182
	v_add_u32_e32 v19, -1, v182
	v_cmp_lt_i32_e32 vcc, v19, v18
	v_add_u32_e32 v21, -2, v182
	s_waitcnt lgkmcnt(0)
	v_add_f32_e32 v20, v16, v17
	v_cndmask_b32_e32 v19, v19, v182, vcc
	v_lshlrev_b32_e32 v19, 2, v19
	ds_bpermute_b32 v19, v19, v20
	v_cmp_eq_u32_e32 vcc, 0, v13
	s_waitcnt lgkmcnt(0)
	v_add_f32_e32 v19, v20, v19
	v_cndmask_b32_e32 v19, v19, v20, vcc
	v_cmp_lt_i32_e32 vcc, v21, v18
	s_nop 1
	v_cndmask_b32_e32 v20, v21, v182, vcc
	v_lshlrev_b32_e32 v20, 2, v20
	ds_bpermute_b32 v20, v20, v19
	v_cmp_gt_u32_e32 vcc, 2, v13
	s_waitcnt lgkmcnt(0)
	v_add_f32_e32 v20, v19, v20
	v_cndmask_b32_e32 v19, v20, v19, vcc
	v_add_u32_e32 v20, -4, v182
	v_cmp_lt_i32_e32 vcc, v20, v18
	s_nop 1
	v_cndmask_b32_e32 v20, v20, v182, vcc
	v_lshlrev_b32_e32 v20, 2, v20
	ds_bpermute_b32 v20, v20, v19
	v_cmp_gt_u32_e32 vcc, 4, v13
	s_waitcnt lgkmcnt(0)
	v_add_f32_e32 v20, v19, v20
	v_cndmask_b32_e32 v19, v20, v19, vcc
	v_add_u32_e32 v20, -8, v182
	v_cmp_lt_i32_e32 vcc, v20, v18
	s_nop 1
	v_cndmask_b32_e32 v20, v20, v182, vcc
	v_lshlrev_b32_e32 v20, 2, v20
	ds_bpermute_b32 v20, v20, v19
	v_cmp_gt_u32_e32 vcc, 8, v13
	s_waitcnt lgkmcnt(0)
	v_add_f32_e32 v20, v19, v20
	v_cndmask_b32_e32 v19, v20, v19, vcc
	v_add_u32_e32 v20, -16, v182
	v_cmp_lt_i32_e32 vcc, v20, v18
	s_nop 1
	v_cndmask_b32_e32 v20, v20, v182, vcc
	v_lshlrev_b32_e32 v20, 2, v20
	ds_bpermute_b32 v20, v20, v19
	v_cmp_gt_u32_e32 vcc, 16, v13
	s_waitcnt lgkmcnt(0)
	v_add_f32_e32 v20, v19, v20
	v_cndmask_b32_e32 v19, v20, v19, vcc
	v_subrev_u32_e32 v20, 32, v182
	v_cmp_lt_i32_e32 vcc, v20, v18
	s_nop 1
	v_cndmask_b32_e32 v18, v20, v182, vcc
	v_lshlrev_b32_e32 v18, 2, v18
	ds_bpermute_b32 v18, v18, v19
	v_cmp_gt_u32_e32 vcc, 32, v13
	s_waitcnt lgkmcnt(0)
	v_add_f32_e32 v18, v19, v18
	v_cndmask_b32_e32 v19, v18, v19, vcc
	v_lshl_or_b32 v18, v182, 2, v187
	ds_bpermute_b32 v20, v18, v19
	v_sub_f32_e32 v18, v19, v16
	v_pk_add_f32 v[22:23], v[18:19], v[16:17] op_sel:[0,1] neg_lo:[0,1] neg_hi:[0,1]
	v_sub_f32_e32 v16, v19, v17
	v_cmp_eq_u32_e32 vcc, 1, v11
	s_waitcnt lgkmcnt(0)
	v_pk_add_f32 v[20:21], v[20:21], v[22:23] op_sel_hi:[0,1] neg_lo:[0,1] neg_hi:[0,1]
	v_cndmask_b32_e32 v17, v19, v21, vcc
	v_cndmask_b32_e32 v16, v16, v20, vcc
	ds_write_b64 v15, v[16:17] offset:36864
.LBB0_1544:
	s_or_b64 exec, exec, s[0:1]
	s_lshl_b32 s0, s42, 7
	s_add_u32 s0, s34, s0
	v_and_b32_e32 v16, 31, v10
	v_lshrrev_b32_e32 v13, 5, v13
	s_addc_u32 s1, s35, 0
	v_lshlrev_b32_e32 v11, 5, v11
	v_mul_u32_u24_e32 v36, 0x110, v14
	v_lshl_add_u64 v[14:15], s[0:1], 0, v[2:3]
	v_lshl_or_b32 v2, v12, 5, v16
	v_lshlrev_b32_e32 v17, 4, v13
	v_and_or_b32 v11, v11, 32, v16
	v_lshlrev_b32_e32 v12, 11, v12
	v_lshlrev_b32_e32 v13, 8, v13
	v_lshl_add_u64 v[20:21], v[14:15], 0, v[4:5]
	v_or3_b32 v4, v13, v12, v11
	v_mul_lo_u32 v2, v2, s86
	v_mul_u32_u24_e32 v16, 0x110, v11
	v_ashrrev_i32_e32 v5, 31, v4
	v_add3_u32 v2, 0, v2, v17
	v_add3_u32 v37, 0, v16, v17
	s_mov_b32 s38, 0
	v_cmp_eq_u32_e64 s[0:1], 0, v10
	v_lshl_add_u64 v[0:1], v[14:15], 0, v[0:1]
	v_lshl_add_u64 v[22:23], v[14:15], 0, v[6:7]
	v_lshl_add_u64 v[24:25], v[14:15], 0, v[8:9]
	v_lshl_add_u64 v[26:27], v[4:5], 2, s[18:19]
	s_mov_b64 s[36:37], -1
	s_waitcnt vmcnt(0) lgkmcnt(0)
	s_barrier
	s_branch .LBB0_1546

; DI float bf2f(bf16_t v) { return __uint_as_float(((unsigned)v) << 16); }
; DI bf16_t f2bf(float x) { unsigned r; asm("v_cvt_pk_bf16_f32 %0, %1, %1" : "=v"(r) : "v"(x)); return (bf16_t)r; }
; DI void ssdA_item(const Params& p, int layer, int it, unsigned char* smem) {
;     ...
;     for (int d = 0; d < 2; ++d) {
;         const float total = d == 0 ? cum[127] : cum[128];
;         { bf16x8 sv[4];
; #pragma unroll
;           for (int q = 0; q < 4; ++q) { const int i = tid + 256 * q, t = i >> 3, c8 = i & 7; sv[q] = ld8(UZ + (size_t)(r0 + t) * 1024 + hd * 64 + c8 * 8); }
; #pragma unroll
;           for (int q = 0; q < 4; ++q) { const int i = tid + 256 * q, t = i >> 3, c8 = i & 7;
;             const float w = __expf(total - cum[d * 128 + t]) * dtv[d * 128 + t];
; #pragma unroll
;             for (int j = 0; j < 8; ++j) XT[(c8 * 8 + j) * TS + t] = f2bf(bf2f((bf16_t)sv[q][j]) * w); } }
.LBB0_1546:
	v_mov_b64_e32 v[4:5], v[190:191]
	v_mov_b64_e32 v[6:7], v[192:193]
	v_mov_b64_e32 v[8:9], v[194:195]
	v_mov_b64_e32 v[10:11], v[196:197]
	s_mov_b64 s[40:41], src_shared_base
	s_cmp_lg_u32 0, -1
	s_cselect_b32 s40, 0, 0
	s_cselect_b32 s39, s41, 0
	s_add_u32 s40, s40, 0x91fc
	s_addc_u32 s41, s39, 0
	s_cmp_lg_u64 s[40:41], 0
	s_cselect_b32 s39, s40, -1
	s_add_i32 s43, 0, 0x9200
	s_and_b64 s[40:41], s[36:37], exec
	s_cselect_b32 s39, s39, s43
	s_lshl_b32 s40, s38, 7
	v_mov_b32_e32 v12, s39
	v_add_u32_e32 v13, s40, v28
	v_add_u32_e32 v14, s40, v29
	ds_read_b32 v38, v12
	v_lshl_add_u32 v12, v13, 2, 0
	v_lshl_add_u32 v13, v14, 2, 0
	ds_read2st64_b32 v[40:41], v12 offset0:136 offset1:144
	ds_read2st64_b32 v[42:43], v13 offset0:136 offset1:144
	v_mov_b64_e32 v[12:13], v[198:199]
	v_mov_b64_e32 v[14:15], v[200:201]
	v_mov_b64_e32 v[16:17], v[202:203]
	v_mov_b64_e32 v[18:19], v[204:205]
	v_add_u32_e32 v44, v33, v36
	s_lshl_b32 s38, s38, 2
	s_waitcnt lgkmcnt(1)
	v_sub_f32_e32 v39, v38, v41
	s_waitcnt lgkmcnt(0)
	v_sub_f32_e32 v41, v38, v43
	v_mul_f32_e32 v39, 0x3fb8aa3b, v39
	v_mul_f32_e32 v41, 0x3fb8aa3b, v41
	v_exp_f32_e32 v39, v39
	v_exp_f32_e32 v41, v41
	v_add_u32_e32 v43, v32, v36
	s_add_i32 s38, s38, s13
	v_mul_f32_e32 v39, v40, v39
	v_mul_f32_e32 v40, v42, v41
	s_mul_i32 s38, s38, 6
	s_add_i32 s38, s38, s42
	s_mul_hi_u32 s39, s38, 34
	s_mul_i32 s38, s38, 34
	s_add_u32 s38, s38, s11
	s_addc_u32 s39, s39, 0
	v_lshlrev_b32_e32 v41, 16, v4
	v_and_b32_e32 v4, 0xffff0000, v4
	v_lshlrev_b32_e32 v42, 16, v5
	v_and_b32_e32 v5, 0xffff0000, v5
	v_lshlrev_b32_e32 v45, 16, v6
	v_and_b32_e32 v6, 0xffff0000, v6
	v_lshlrev_b32_e32 v46, 16, v7
	v_and_b32_e32 v7, 0xffff0000, v7
	v_lshlrev_b32_e32 v47, 16, v8
	v_and_b32_e32 v8, 0xffff0000, v8
	v_lshlrev_b32_e32 v48, 16, v9
	v_and_b32_e32 v9, 0xffff0000, v9
	v_mul_f32_e32 v41, v39, v41
	v_mul_f32_e32 v4, v39, v4
	v_lshlrev_b32_e32 v49, 16, v10
	v_mul_f32_e32 v42, v39, v42
	v_mul_f32_e32 v5, v39, v5
	v_mul_f32_e32 v45, v39, v45
	v_mul_f32_e32 v6, v39, v6
	v_mul_f32_e32 v46, v39, v46
	v_mul_f32_e32 v7, v39, v7
	v_mul_f32_e32 v39, v40, v47
	v_mul_f32_e32 v8, v40, v8
	v_mul_f32_e32 v47, v40, v48
	v_mul_f32_e32 v9, v40, v9
	v_cvt_pk_bf16_f32 v41, v41, v41
	v_cvt_pk_bf16_f32 v4, v4, v4
	v_mul_f32_e32 v48, v40, v49
	v_cvt_pk_bf16_f32 v42, v42, v42
	v_cvt_pk_bf16_f32 v5, v5, v5
	v_cvt_pk_bf16_f32 v45, v45, v45
	v_cvt_pk_bf16_f32 v6, v6, v6
	v_cvt_pk_bf16_f32 v46, v46, v46
	v_cvt_pk_bf16_f32 v7, v7, v7
	v_cvt_pk_bf16_f32 v39, v39, v39
	v_cvt_pk_bf16_f32 v8, v8, v8
	v_cvt_pk_bf16_f32 v47, v47, v47
	v_cvt_pk_bf16_f32 v9, v9, v9
	ds_write_b16 v43, v41 offset:17408
	ds_write_b16 v43, v4 offset:17680
	ds_write_b16 v43, v42 offset:17952
	ds_write_b16 v43, v5 offset:18224
	ds_write_b16 v43, v45 offset:18496
	ds_write_b16 v43, v6 offset:18768
	ds_write_b16 v43, v46 offset:19040
	ds_write_b16 v43, v7 offset:19312
	ds_write_b16 v44, v39 offset:17408
	ds_write_b16 v44, v8 offset:17680
	ds_write_b16 v44, v47 offset:17952
	ds_write_b16 v44, v9 offset:18224
	v_cvt_pk_bf16_f32 v4, v48, v48
	ds_write_b16 v44, v4 offset:18496
	v_and_b32_e32 v4, 0xffff0000, v10
	v_mul_f32_e32 v4, v40, v4
	v_cvt_pk_bf16_f32 v4, v4, v4
	ds_write_b16 v44, v4 offset:18768
	v_add_u32_e32 v4, s40, v30
	v_lshl_add_u32 v4, v4, 2, 0
	ds_read2st64_b32 v[4:5], v4 offset0:136 offset1:144
	v_lshlrev_b32_e32 v6, 16, v11
	v_mul_f32_e32 v6, v40, v6
	v_cvt_pk_bf16_f32 v6, v6, v6
	ds_write_b16 v44, v6 offset:19040
	s_waitcnt lgkmcnt(1)
	v_sub_f32_e32 v5, v38, v5
	v_mul_f32_e32 v5, 0x3fb8aa3b, v5
	v_exp_f32_e32 v5, v5
	v_and_b32_e32 v6, 0xffff0000, v11
	v_mul_f32_e32 v6, v40, v6
	v_cvt_pk_bf16_f32 v6, v6, v6
	ds_write_b16 v44, v6 offset:19312
	v_mul_f32_e32 v6, v4, v5
	v_lshlrev_b32_e32 v4, 16, v12
	v_mul_f32_e32 v4, v6, v4
	v_cvt_pk_bf16_f32 v4, v4, v4
	v_add_u32_e32 v7, v34, v36
	ds_write_b16 v7, v4 offset:17408
	v_and_b32_e32 v4, 0xffff0000, v12
	v_mul_f32_e32 v4, v6, v4
	v_cvt_pk_bf16_f32 v4, v4, v4
	ds_write_b16 v7, v4 offset:17680
	v_lshlrev_b32_e32 v4, 16, v13
	v_mul_f32_e32 v4, v6, v4
	v_cvt_pk_bf16_f32 v4, v4, v4
	ds_write_b16 v7, v4 offset:17952
	v_and_b32_e32 v4, 0xffff0000, v13
	v_mul_f32_e32 v4, v6, v4
	v_cvt_pk_bf16_f32 v4, v4, v4
	ds_write_b16 v7, v4 offset:18224
	v_lshlrev_b32_e32 v4, 16, v14
	v_mul_f32_e32 v4, v6, v4
	v_cvt_pk_bf16_f32 v4, v4, v4
	ds_write_b16 v7, v4 offset:18496
	v_and_b32_e32 v4, 0xffff0000, v14
	v_mul_f32_e32 v4, v6, v4
	v_cvt_pk_bf16_f32 v4, v4, v4
	ds_write_b16 v7, v4 offset:18768
	v_add_u32_e32 v4, s40, v31
	v_lshl_add_u32 v4, v4, 2, 0
	ds_read2st64_b32 v[4:5], v4 offset0:136 offset1:144
	v_lshlrev_b32_e32 v8, 16, v15
	v_mul_f32_e32 v8, v6, v8
	v_cvt_pk_bf16_f32 v8, v8, v8
	ds_write_b16 v7, v8 offset:19040
	s_waitcnt lgkmcnt(1)
	v_sub_f32_e32 v5, v38, v5
	v_mul_f32_e32 v5, 0x3fb8aa3b, v5
	v_exp_f32_e32 v5, v5
	v_and_b32_e32 v8, 0xffff0000, v15
	v_mul_f32_e32 v6, v6, v8
	v_cvt_pk_bf16_f32 v6, v6, v6
	v_mul_f32_e32 v4, v4, v5
	v_lshlrev_b32_e32 v5, 16, v16
	v_mul_f32_e32 v5, v4, v5
	ds_write_b16 v7, v6 offset:19312
	v_cvt_pk_bf16_f32 v5, v5, v5
	v_add_u32_e32 v6, v35, v36
	ds_write_b16 v6, v5 offset:17408
	v_and_b32_e32 v5, 0xffff0000, v16
	v_mul_f32_e32 v5, v4, v5
	v_cvt_pk_bf16_f32 v5, v5, v5
	ds_write_b16 v6, v5 offset:17680
	v_lshlrev_b32_e32 v5, 16, v17
	v_mul_f32_e32 v5, v4, v5
	v_cvt_pk_bf16_f32 v5, v5, v5
	ds_write_b16 v6, v5 offset:17952
	v_and_b32_e32 v5, 0xffff0000, v17
	v_mul_f32_e32 v5, v4, v5
	v_cvt_pk_bf16_f32 v5, v5, v5
	ds_write_b16 v6, v5 offset:18224
	v_lshlrev_b32_e32 v5, 16, v18
	v_mul_f32_e32 v5, v4, v5
	v_cvt_pk_bf16_f32 v5, v5, v5
	ds_write_b16 v6, v5 offset:18496
	v_and_b32_e32 v5, 0xffff0000, v18
	v_mul_f32_e32 v5, v4, v5
	v_cvt_pk_bf16_f32 v5, v5, v5
	ds_write_b16 v6, v5 offset:18768
	v_lshlrev_b32_e32 v5, 16, v19
	v_mul_f32_e32 v5, v4, v5
	v_cvt_pk_bf16_f32 v5, v5, v5
	ds_write_b16 v6, v5 offset:19040
	v_and_b32_e32 v5, 0xffff0000, v19
	v_mul_f32_e32 v4, v4, v5
	v_cvt_pk_bf16_f32 v4, v4, v4
	ds_write_b16 v6, v4 offset:19312
	s_waitcnt lgkmcnt(0)
	s_barrier
; #define MFMA(a, b, c) __builtin_amdgcn_mfma_f32_32x32x16_bf16((a), (b), (c), 0, 0, 0)
; DI int crow(int reg, int h) { return (reg & 3) + 8 * (reg >> 2) + 4 * h; }
; DI f32x16 zero16() { f32x16 z; _Pragma("unroll") for (int i = 0; i < 16; ++i) z[i] = 0.f; return z; }
; DI void ssdA_item(const Params& p, int layer, int it, unsigned char* smem) {
;     ...
;         const int pt = wave >> 1, nt = wave & 1;
;         f32x16 acc = zero16();
; #pragma unroll
;         for (int ks = 0; ks < 8; ++ks) acc = MFMA(ld8(XT + (32 * pt + li) * TS + 16 * ks + 8 * lh), ld8(BT + (32 * nt + li) * TS + 16 * ks + 8 * lh), acc);
;         float* st = ST + ((((size_t)d * 4 + b) * 6 + hd) * NCHK + cidx) * 4096;
; #pragma unroll
;         for (int reg = 0; reg < 16; ++reg) st[(32 * pt + crow(reg, lh)) * 64 + 32 * nt + li] = acc[reg];
;         if (tid == 0) DEC[(((size_t)d * 4 + b) * 6 + hd) * NCHK + cidx] = __expf(total);
;         __syncthreads();
	ds_read_b128 v[4:7], v2 offset:17408
	ds_read_b128 v[8:11], v37
	s_waitcnt lgkmcnt(0)
	v_mfma_f32_32x32x16_bf16 v[4:19], v[4:7], v[8:11], 0
	ds_read_b128 v[40:43], v2 offset:17440
	ds_read_b128 v[44:47], v37 offset:32
	s_lshl_b64 s[40:41], s[38:39], 14
	s_waitcnt lgkmcnt(0)
	v_mfma_f32_32x32x16_bf16 v[4:19], v[40:43], v[44:47], v[4:19]
	ds_read_b128 v[40:43], v2 offset:17472
	ds_read_b128 v[44:47], v37 offset:64
	s_waitcnt lgkmcnt(0)
	v_mfma_f32_32x32x16_bf16 v[4:19], v[40:43], v[44:47], v[4:19]
	ds_read_b128 v[40:43], v2 offset:17504
	ds_read_b128 v[44:47], v37 offset:96
	s_waitcnt lgkmcnt(0)
	v_mfma_f32_32x32x16_bf16 v[4:19], v[40:43], v[44:47], v[4:19]
	ds_read_b128 v[40:43], v2 offset:17536
	ds_read_b128 v[44:47], v37 offset:128
	s_waitcnt lgkmcnt(0)
	v_mfma_f32_32x32x16_bf16 v[4:19], v[40:43], v[44:47], v[4:19]
	ds_read_b128 v[40:43], v2 offset:17568
	ds_read_b128 v[44:47], v37 offset:160
	s_waitcnt lgkmcnt(0)
	v_mfma_f32_32x32x16_bf16 v[4:19], v[40:43], v[44:47], v[4:19]
	ds_read_b128 v[40:43], v2 offset:17600
	ds_read_b128 v[44:47], v37 offset:192
	s_waitcnt lgkmcnt(0)
	v_mfma_f32_32x32x16_bf16 v[4:19], v[40:43], v[44:47], v[4:19]
	ds_read_b128 v[40:43], v2 offset:17632
	ds_read_b128 v[44:47], v37 offset:224
	s_waitcnt lgkmcnt(0)
	v_mfma_f32_32x32x16_bf16 v[4:19], v[40:43], v[44:47], v[4:19]
	v_lshl_add_u64 v[40:41], v[26:27], 0, s[40:41]
	s_nop 10
	global_store_dword v[40:41], v4, off
	global_store_dword v[40:41], v5, off offset:256
	global_store_dword v[40:41], v6, off offset:512
	global_store_dword v[40:41], v7, off offset:768
	global_store_dword v[40:41], v8, off offset:2048
	global_store_dword v[40:41], v9, off offset:2304
	global_store_dword v[40:41], v10, off offset:2560
	global_store_dword v[40:41], v11, off offset:2816
	v_add_co_u32_e32 v4, vcc, s82, v40
	s_nop 1
	v_addc_co_u32_e32 v5, vcc, 0, v41, vcc
	global_store_dword v[4:5], v12, off
	global_store_dword v[4:5], v13, off offset:256
	global_store_dword v[4:5], v14, off offset:512
	global_store_dword v[4:5], v15, off offset:768
	global_store_dword v[4:5], v16, off offset:2048
	global_store_dword v[4:5], v17, off offset:2304
	global_store_dword v[4:5], v18, off offset:2560
	global_store_dword v[4:5], v19, off offset:2816
	s_and_saveexec_b64 s[40:41], s[0:1]
	s_cbranch_execz .LBB0_1545
	v_mul_f32_e32 v4, 0x3fb8aa3b, v38
	v_exp_f32_e32 v4, v4
	s_lshl_b64 s[38:39], s[38:39], 2
	s_add_u32 s38, s15, s38
	s_addc_u32 s39, s12, s39
	global_store_dword v3, v4, s[38:39]
	s_branch .LBB0_1545
